# combo16 + final RMSNorm loop: the four loop-invariant norm-weight loads hoisted out of the row loop into persistent registers (6 loads per row instead of 10)
# baseline (speedup 1.0000x reference)
.LBB0_43:
	s_and_b64 vcc, exec, s[6:7]
	s_cbranch_vccz .LBB0_47
	s_cmp_lg_u32 s58, 45
	s_cselect_b64 s[6:7], -1, 0
	s_cmp_gt_i32 s14, 0xbfff
	s_cselect_b64 s[8:9], -1, 0
	s_or_b64 s[6:7], s[6:7], s[8:9]
	s_and_b64 vcc, exec, s[6:7]
	s_cbranch_vccnz .LBB0_47
	s_load_dwordx2 s[6:7], s[0:1], 0xa0
	v_lshlrev_b32_e32 v0, 5, v66
	s_ashr_i32 s15, s14, 31
	v_mov_b32_e32 v5, v1
	v_or_b32_e32 v4, 0x800, v0
	s_ashr_i32 s11, s10, 31
	s_lshl_b64 s[16:17], s[14:15], 11
	s_waitcnt lgkmcnt(0)
	v_lshl_add_u64 v[2:3], s[6:7], 0, v[0:1]
	v_lshl_add_u64 v[4:5], s[6:7], 0, v[4:5]
	s_lshl_b64 s[6:7], s[14:15], 6
	s_lshl_b64 s[8:9], s[10:11], 6
	v_lshl_or_b32 v6, v66, 4, s16
	v_mov_b32_e32 v7, s17
	s_lshl_b64 s[16:17], s[10:11], 11
	s_lshl_b64 s[18:19], s[14:15], 12
	s_add_u32 s18, s76, s18
	s_addc_u32 s19, s77, s19
	v_lshl_add_u64 v[8:9], s[18:19], 0, v[0:1]
	s_mov_b64 s[18:19], 0x810
	v_lshl_add_u64 v[8:9], v[8:9], 0, s[18:19]
	s_lshl_b64 s[18:19], s[10:11], 12
	s_mov_b32 s11, s14
	global_load_dwordx4 v[56:59], v[2:3], off
	global_load_dwordx4 v[34:37], v[2:3], off offset:16
	global_load_dwordx4 v[48:51], v[4:5], off
	global_load_dwordx4 v[52:55], v[4:5], off offset:16
.LBB0_46:
	s_add_u32 s20, s78, s6
	v_lshl_add_u64 v[14:15], s[78:79], 0, v[6:7]
	s_mov_b32 s15, 0x3000000
	s_addc_u32 s21, s79, s7
	v_add_co_u32_e32 v38, vcc, s15, v14
	v_mov_b32_e32 v0, 0x1f800000
	v_addc_co_u32_e32 v39, vcc, 0, v15, vcc
	global_load_dwordx4 v[14:17], v0, s[20:21]
	global_load_dwordx4 v[18:21], v[38:39], off
	s_add_u32 s20, s20, 0x1f800000
	s_addc_u32 s21, s21, 0
	global_load_dwordx4 v[22:25], v1, s[20:21] offset:16
	global_load_dwordx4 v[26:29], v1, s[20:21] offset:32
	global_load_dwordx4 v[30:33], v1, s[20:21] offset:48
	global_load_dwordx4 v[44:47], v[38:39], off offset:1024
	s_add_i32 s11, s11, s10
	s_add_u32 s6, s6, s8
	s_addc_u32 s7, s7, s9
	v_lshl_add_u64 v[6:7], v[6:7], 0, s[16:17]
	s_cmp_gt_i32 s11, 0xbfff
	s_waitcnt vmcnt(0)
	v_mov_b32_e32 v40, v15
	v_mov_b32_e32 v41, v16
	v_mov_b32_e32 v15, v17
	v_pk_add_f32 v[14:15], v[40:41], v[14:15]
	s_waitcnt vmcnt(3)
	v_mov_b32_e32 v40, v23
	v_mov_b32_e32 v41, v24
	v_mov_b32_e32 v23, v25
	v_pk_add_f32 v[22:23], v[40:41], v[22:23]
	v_pk_add_f32 v[14:15], v[14:15], v[14:15] op_sel:[0,1] op_sel_hi:[1,0]
	v_pk_add_f32 v[22:23], v[22:23], v[22:23] op_sel:[0,1] op_sel_hi:[1,0]
	s_waitcnt vmcnt(2)
	v_add_f32_e32 v24, v26, v27
	v_add_f32_e32 v26, v28, v29
	s_waitcnt vmcnt(1)
	v_mov_b32_e32 v25, v32
	v_mov_b32_e32 v27, v33
	v_mov_b32_e32 v15, v30
	v_mov_b32_e32 v23, v31
	v_pk_add_f32 v[24:25], v[24:25], v[26:27]
	v_pk_add_f32 v[14:15], v[14:15], v[22:23]
	v_lshlrev_b32_e32 v16, 16, v18
	v_pk_add_f32 v[14:15], v[14:15], v[24:25]
	v_and_b32_e32 v17, 0xffff0000, v18
	v_add_f32_e32 v0, v14, v15
	v_fmamk_f32 v0, v0, 0x3a800000, v223
	v_rsq_f32_e32 v0, v0
	v_lshlrev_b32_e32 v18, 16, v19
	v_and_b32_e32 v19, 0xffff0000, v19
	v_lshlrev_b32_e32 v42, 16, v20
	v_and_b32_e32 v43, 0xffff0000, v20
	v_lshlrev_b32_e32 v20, 16, v21
	v_and_b32_e32 v21, 0xffff0000, v21
	v_pk_mul_f32 v[14:15], v[0:1], v[16:17] op_sel_hi:[0,1]
	v_pk_mul_f32 v[16:17], v[0:1], v[18:19] op_sel_hi:[0,1]
	v_pk_mul_f32 v[18:19], v[0:1], v[42:43] op_sel_hi:[0,1]
	v_pk_mul_f32 v[20:21], v[0:1], v[20:21] op_sel_hi:[0,1]
	v_pk_mul_f32 v[12:13], v[58:59], v[16:17]
	v_pk_mul_f32 v[10:11], v[56:57], v[14:15]
	s_waitcnt vmcnt(0)
	v_pk_mul_f32 v[16:17], v[36:37], v[20:21]
	v_pk_mul_f32 v[14:15], v[34:35], v[18:19]
	global_store_dwordx4 v[8:9], v[10:13], off offset:-2064 nt
	global_store_dwordx4 v[8:9], v[14:17], off offset:-2048 nt
	v_lshlrev_b32_e32 v22, 16, v44
	v_and_b32_e32 v23, 0xffff0000, v44
	v_lshlrev_b32_e32 v10, 16, v45
	v_and_b32_e32 v11, 0xffff0000, v45
	v_lshlrev_b32_e32 v24, 16, v46
	v_and_b32_e32 v25, 0xffff0000, v46
	v_lshlrev_b32_e32 v12, 16, v47
	v_and_b32_e32 v13, 0xffff0000, v47
	v_pk_mul_f32 v[22:23], v[0:1], v[22:23] op_sel_hi:[0,1]
	v_pk_mul_f32 v[10:11], v[0:1], v[10:11] op_sel_hi:[0,1]
	v_pk_mul_f32 v[24:25], v[0:1], v[24:25] op_sel_hi:[0,1]
	v_pk_mul_f32 v[26:27], v[0:1], v[12:13] op_sel_hi:[0,1]
	v_pk_mul_f32 v[12:13], v[50:51], v[10:11]
	v_pk_mul_f32 v[10:11], v[48:49], v[22:23]
	v_pk_mul_f32 v[16:17], v[54:55], v[26:27]
	v_pk_mul_f32 v[14:15], v[52:53], v[24:25]
	global_store_dwordx4 v[8:9], v[10:13], off offset:-16 nt
	global_store_dwordx4 v[8:9], v[14:17], off nt
	v_lshl_add_u64 v[8:9], v[8:9], 0, s[18:19]
	s_cbranch_scc0 .LBB0_46
